# residual-tile cache-warming touches issued mid k-loop in out-proj and ffn-out GEMMs
# baseline (speedup 1.0000x reference)
.LBB0_53:
	s_cmpk_eq_i32 s0, 0xa00
	s_cbranch_scc0 .Lepipf_ffo
	v_readlane_b32 s42, v242, 27
	v_readlane_b32 s43, v242, 28
	s_mul_i32 s44, s7, 0xc0000
	s_lshl_b32 s45, s6, 2
	s_add_u32 s44, s44, s45
	s_add_u32 s42, s42, s44
	s_addc_u32 s43, s43, 0
	v_lshrrev_b32_e32 v250, 2, v132
	v_and_b32_e32 v251, 3, v132
	v_lshlrev_b32_e32 v250, 12, v250
	v_lshl_add_u32 v250, v251, 7, v250
	global_load_dword v251, v250, s[42:43]
	s_add_u32 s42, s42, 0x40000
	s_addc_u32 s43, s43, 0
	global_load_dword v251, v250, s[42:43]
	s_add_u32 s42, s42, 0x40000
	s_addc_u32 s43, s43, 0
	global_load_dword v251, v250, s[42:43]

.LBB0_128:
	s_cmpk_eq_i32 s6, 0x300
	s_cbranch_scc0 .Lepipf_out
	v_readlane_b32 s42, v242, 25
	v_readlane_b32 s43, v242, 26
	s_lshl_b32 s44, s0, 12
	s_lshl_b32 s45, s4, 2
	s_add_u32 s44, s44, s45
	s_add_u32 s42, s42, s44
	s_addc_u32 s43, s43, 0
	v_lshrrev_b32_e32 v250, 2, v132
	v_and_b32_e32 v251, 3, v132
	v_lshlrev_b32_e32 v250, 12, v250
	v_lshl_add_u32 v250, v251, 7, v250
	global_load_dword v251, v250, s[42:43]
	s_add_u32 s42, s42, 0x40000
	s_addc_u32 s43, s43, 0
	global_load_dword v251, v250, s[42:43]
	s_add_u32 s42, s42, 0x40000
	s_addc_u32 s43, s43, 0
	global_load_dword v251, v250, s[42:43]
